# in-projection GEMM: one static s_setprio 1 for the younger wave half before the main loop, per-phase flips deleted, priority reset after the phase
# baseline (speedup 1.0000x reference)
.LBB0_144:
	s_add_i32 m0, s23, 0x18000
	v_lshl_add_u64 v[6:7], v[6:7], 0, s[62:63]
	s_waitcnt vmcnt(2)
	s_barrier
	global_load_lds_dwordx4 v[6:7], off
	v_lshl_add_u64 v[6:7], v[8:9], 0, s[62:63]
	s_add_i32 m0, s23, 0x1a000
	s_add_i32 s27, s23, 0x8000
	global_load_lds_dwordx4 v[6:7], off
	v_lshl_add_u64 v[6:7], v[10:11], 0, s[62:63]
	s_mov_b32 m0, s27
	s_add_i32 s28, s23, 0xa000
	global_load_lds_dwordx4 v[6:7], off
	v_lshl_add_u64 v[6:7], v[12:13], 0, s[62:63]
	s_mov_b32 m0, s28
	s_lshl_b32 s5, s5, 5
	global_load_lds_dwordx4 v[6:7], off
	v_lshl_add_u64 v[6:7], v[2:3], 0, s[84:85]
	s_add_i32 m0, s23, 0x1c000
	v_lshl_add_u64 v[8:9], v[6:7], 0, v[138:139]
	global_load_lds_dwordx4 v[8:9], off
	v_lshl_add_u64 v[6:7], v[6:7], 0, v[134:135]
	s_add_i32 m0, s23, 0x1e000
	s_and_b32 s5, s5, 0x60
	global_load_lds_dwordx4 v[6:7], off
	v_lshrrev_b32_e32 v7, 1, v0
	v_and_b32_e32 v7, 24, v7
	v_and_b32_e32 v6, 15, v0
	v_lshlrev_b32_e32 v8, 1, v7
	v_lshlrev_b32_e32 v0, 2, v0
	v_lshl_or_b32 v162, s6, 6, v6
	v_lshl_or_b32 v6, v6, 6, v8
	s_lshl_b32 s6, s6, 13
	v_and_b32_e32 v0, 32, v0
	v_bitop3_b32 v8, v6, s6, v0 bitop3:0xde
	s_lshl_b32 s6, s5, 7
	v_bitop3_b32 v163, v6, s6, v0 bitop3:0xde
	v_lshlrev_b32_e32 v0, 14, v14
	v_and_b32_e32 v0, 0xffff8000, v0
	v_lshl_add_u32 v0, v15, 11, v0
	v_and_b32_e32 v6, 1, v14
	v_lshl_or_b32 v0, v6, 6, v0
	v_lshl_add_u32 v146, v16, 1, v0
	v_lshlrev_b32_e32 v0, 14, v18
	v_and_b32_e32 v0, 0xffff8000, v0
	s_mov_b64 s[8:9], 0x8b89000
	s_waitcnt vmcnt(6)
	v_lshl_add_u32 v0, v17, 11, v0
	v_and_b32_e32 v6, 1, v18
	v_lshl_add_u64 v[142:143], v[130:131], 0, s[8:9]
	s_mov_b64 s[8:9], 0x12b89000
	s_cmpk_lt_u32 s4, 0x100
	v_or_b32_e32 v164, s5, v7
	v_lshl_or_b32 v0, v6, 6, v0
	v_readlane_b32 s4, v254, 41
	s_movk_i32 s40, 0xec00
	v_lshl_add_u64 v[144:145], v[130:131], 0, s[8:9]
	s_cselect_b64 s[14:15], -1, 0
	v_mov_b32_e32 v147, v1
	v_lshl_add_u32 v148, v19, 1, v0
	v_mov_b32_e32 v149, v1
	s_mov_b32 s29, 0
	v_add_u32_e32 v165, 0, v8
	v_readlane_b32 s7, v254, 18
	s_mov_b32 s6, s4
	s_movk_i32 s34, 0x161
	s_movk_i32 s35, 0x9ff
	s_movk_i32 s36, 0x980
	s_mov_b32 s41, -1
	s_barrier
	v_readlane_b32 s5, v254, 42
	s_and_b64 vcc, exec, s[12:13]
	s_cbranch_vccz .Lg1_noprio
	s_setprio 1
.Lg1_noprio:
	s_mov_b32 s98, 0
	s_branch .LBB0_147

.LBB0_252:
	s_setprio 0
	s_waitcnt vmcnt(0)
	v_readlane_b32 s41, v255, 12
	s_barrier
